# grid barrier: the L1 invalidate (acquire) issued once at barrier entry, after the workgroup's loads drained, instead of after the release flag is seen (L1 stays empty while waiting)
# baseline (speedup 1.0000x reference)
; __device__ __forceinline__ unsigned xb_ld(unsigned* p)              { return __hip_atomic_load(p, __ATOMIC_RELAXED, __HIP_MEMORY_SCOPE_AGENT); }
; __device__ __forceinline__ void xcd_barrier_complete(unsigned* bar, unsigned x, unsigned& nloc, unsigned& nx) {
;     const unsigned G = gridDim.x * gridDim.y * gridDim.z;
;     unsigned sum, cnt, mine, sp = 0u;
;     for (;;) {
;         sum = 0u; cnt = 0u; mine = 0u;
; #pragma unroll
;         for (unsigned j = 0; j < 16; ++j) { const unsigned c = xb_ld(&bar[XB_XCNT(j)]); sum += c; cnt += (c > 0u) ? 1u : 0u; mine = (j == x) ? c : mine; }
; __device__ __forceinline__ void xcd_barrier(const XcdBarrier& b) {
;     asm volatile("s_waitcnt vmcnt(0)" ::: "memory");
;     __syncthreads();
;     if (threadIdx.x == 0) {
;         unsigned* bar = b.bar;
;         __builtin_amdgcn_s_waitcnt(0);
;         unsigned nloc = b.st[0], nx = b.st[1];
;         if (nloc == 0u) { xcd_barrier_complete(bar, b.x, nloc, nx); b.st[0] = nloc; b.st[1] = nx; }
.LBB0_22:
	s_waitcnt vmcnt(0)
	s_waitcnt lgkmcnt(0)
	s_barrier
	s_mov_b64 s[4:5], exec
	v_readlane_b32 s2, v249, 5
	v_readlane_b32 s3, v249, 6
	s_and_b64 s[2:3], s[4:5], s[2:3]
	s_mov_b64 exec, s[2:3]
	s_cbranch_execz .LBB0_74
	s_load_dwordx2 s[2:3], s[88:89], 0xf8
	s_waitcnt vmcnt(0) expcnt(0) lgkmcnt(0)
	buffer_inv sc1
	s_add_u32 s6, s2, 0x104200
	s_addc_u32 s7, s3, 0
	s_add_i32 s2, 0, 0x20020
	v_mov_b32_e32 v2, s2
	ds_read_b32 v4, v2
	s_add_i32 s2, 0, 0x20024
	v_mov_b32_e32 v2, s2
	ds_read_b32 v2, v2
	s_waitcnt lgkmcnt(1)
	v_cmp_ne_u32_e32 vcc, 0, v4
	s_cbranch_vccnz .LBB0_38
	s_load_dwordx2 s[68:69], s[88:89], 0xf8
	v_readlane_b32 s30, v249, 0
	v_readlane_b32 s31, v249, 1
	s_load_dwordx2 s[2:3], s[30:31], 0x4
	v_mov_b32_e32 v18, 0
	s_waitcnt lgkmcnt(0)
	s_add_u32 s8, s68, 0x104400
	s_addc_u32 s9, s69, 0
	s_add_u32 s40, s68, 0x104500
	s_addc_u32 s41, s69, 0
	s_add_u32 s42, s68, 0x104600
	s_addc_u32 s43, s69, 0
	s_add_u32 s44, s68, 0x104700
	s_addc_u32 s45, s69, 0
	s_add_u32 s46, s68, 0x104800
	s_addc_u32 s47, s69, 0
	s_add_u32 s48, s68, 0x104900
	s_addc_u32 s49, s69, 0
	s_add_u32 s50, s68, 0x104a00
	s_addc_u32 s51, s69, 0
	s_add_u32 s52, s68, 0x104b00
	s_addc_u32 s53, s69, 0
	s_add_u32 s54, s68, 0x104c00
	s_addc_u32 s55, s69, 0
	s_add_u32 s56, s68, 0x104d00
	s_addc_u32 s57, s69, 0
	s_add_u32 s58, s68, 0x104e00
	s_addc_u32 s59, s69, 0
	s_add_u32 s60, s68, 0x104f00
	s_addc_u32 s61, s69, 0
	s_add_u32 s62, s68, 0x105000
	s_addc_u32 s63, s69, 0
	s_add_u32 s64, s68, 0x105100
	s_addc_u32 s65, s69, 0
	s_add_u32 s66, s68, 0x105200
	s_addc_u32 s67, s69, 0
	s_add_u32 s68, s68, 0x105300
	s_mul_i32 s2, s2, s85
	s_addc_u32 s69, s69, 0
	s_mul_i32 s2, s2, s3
	s_mov_b32 s3, 1
	s_branch .LBB0_26

; __device__ __forceinline__ unsigned xb_ld(unsigned* p)              { return __hip_atomic_load(p, __ATOMIC_RELAXED, __HIP_MEMORY_SCOPE_AGENT); }
; #define XB_SPIN(cond, bar) do { unsigned _sp = 0; while (cond) { __builtin_amdgcn_s_sleep(1); \
;     if ((++_sp & 255u) == 0u) { if (xb_ld(&(bar)[XB_TMO])) break; if (_sp > XB_SPIN_CAP) { atomicAdd(&(bar)[XB_TMO], 1u); break; } } } } while (0)
; __device__ __forceinline__ void xcd_barrier(const XcdBarrier& b) {
;     ...
;         } else {
;             XB_SPIN(xb_ld(&bar[XB_XGEN(b.x)]) == gen, bar);
;             __builtin_amdgcn_fence(__ATOMIC_ACQUIRE, "agent");
;             asm volatile("s_waitcnt vmcnt(0)" ::: "memory");
.LBB0_53:
	s_or_b64 exec, exec, s[42:43]
	s_waitcnt vmcnt(0)
	s_waitcnt vmcnt(0)

; __device__ __forceinline__ unsigned xb_ld(unsigned* p)              { return __hip_atomic_load(p, __ATOMIC_RELAXED, __HIP_MEMORY_SCOPE_AGENT); }
; __device__ __forceinline__ unsigned xb_add(unsigned* p, unsigned v) { return __hip_atomic_fetch_add(p, v, __ATOMIC_RELAXED, __HIP_MEMORY_SCOPE_AGENT); }
; #define XB_SPIN(cond, bar) do { unsigned _sp = 0; while (cond) { __builtin_amdgcn_s_sleep(1); \
;     if ((++_sp & 255u) == 0u) { if (xb_ld(&(bar)[XB_TMO])) break; if (_sp > XB_SPIN_CAP) { atomicAdd(&(bar)[XB_TMO], 1u); break; } } } } while (0)
; __device__ __forceinline__ void xcd_barrier(const XcdBarrier& b) {
;     ...
;             __builtin_amdgcn_fence(__ATOMIC_RELEASE, "agent");
;             asm volatile("s_waitcnt vmcnt(0)" ::: "memory");
;             const unsigned og = xb_add(&bar[XB_TOP], 1u);
;             const unsigned tg = og / nx;
;             if (og + 1u == (tg + 1u) * nx) xb_add(&bar[XB_TOPGEN], 1u);
;             else XB_SPIN(xb_ld(&bar[XB_TOPGEN]) == tg, bar);
;             __builtin_amdgcn_fence(__ATOMIC_ACQUIRE, "agent");
;             xb_add(&bar[XB_XGEN(b.x)], 1u);
;             asm volatile("s_waitcnt vmcnt(0)" ::: "memory");
.LBB0_71:
	s_or_b64 exec, exec, s[6:7]
	s_mov_b64 s[6:7], exec
	v_mbcnt_lo_u32_b32 v2, s6, 0
	v_mbcnt_hi_u32_b32 v2, s7, v2
	v_cmp_eq_u32_e32 vcc, 0, v2
	s_waitcnt vmcnt(0)
	s_and_saveexec_b64 s[40:41], vcc
	s_cbranch_execz .LBB0_73
	s_bcnt1_i32_b64 s2, s[6:7]
	v_mov_b32_e32 v2, 0
	v_mov_b32_e32 v3, s2
	global_atomic_add v2, v3, s[8:9]

; __device__ __forceinline__ void xcd_barrier(const XcdBarrier& b) {
;     asm volatile("s_waitcnt vmcnt(0)" ::: "memory");
;     __syncthreads();
;     if (threadIdx.x == 0) {
;         unsigned* bar = b.bar;
;         __builtin_amdgcn_s_waitcnt(0);
;         unsigned nloc = b.st[0], nx = b.st[1];
;         if (nloc == 0u) { xcd_barrier_complete(bar, b.x, nloc, nx); b.st[0] = nloc; b.st[1] = nx; }
.LBB0_217:
.LBB0_218:
	s_waitcnt vmcnt(0)
	s_lshl_b32 s4, s76, 6
	s_mov_b32 s5, 0
	s_barrier
	s_mov_b64 s[6:7], exec
	v_readlane_b32 s2, v249, 5
	v_readlane_b32 s3, v249, 6
	s_and_b64 s[2:3], s[6:7], s[2:3]
	s_mov_b64 exec, s[2:3]
	s_cbranch_execz .LBB0_270
	v_readlane_b32 s2, v249, 3
	v_readlane_b32 s3, v249, 4
	s_add_u32 s8, s2, 0x104200
	s_addc_u32 s9, s3, 0
	s_add_i32 s2, 0, 0x20020
	v_mov_b32_e32 v2, s2
	s_waitcnt vmcnt(0) expcnt(0) lgkmcnt(0)
	buffer_inv sc1
	ds_read_b32 v4, v2
	s_add_i32 s2, 0, 0x20024
	v_mov_b32_e32 v2, s2
	ds_read_b32 v2, v2
	s_waitcnt lgkmcnt(1)
	v_cmp_ne_u32_e32 vcc, 0, v4
	s_cbranch_vccnz .LBB0_234
	v_readlane_b32 s44, v249, 3
	v_readlane_b32 s45, v249, 4
	s_add_u32 s10, s44, 0x104400
	s_addc_u32 s11, s45, 0
	s_add_u32 s12, s44, 0x104500
	s_addc_u32 s13, s45, 0
	s_add_u32 s14, s44, 0x104600
	s_addc_u32 s15, s45, 0
	s_add_u32 s16, s44, 0x104700
	s_addc_u32 s17, s45, 0
	s_add_u32 s18, s44, 0x104800
	s_addc_u32 s19, s45, 0
	s_add_u32 s20, s44, 0x104900
	s_addc_u32 s21, s45, 0
	s_add_u32 s22, s44, 0x104a00
	s_addc_u32 s23, s45, 0
	s_add_u32 s24, s44, 0x104b00
	s_addc_u32 s25, s45, 0
	s_add_u32 s26, s44, 0x104c00
	s_addc_u32 s27, s45, 0
	s_add_u32 s30, s44, 0x104d00
	s_addc_u32 s31, s45, 0
	s_add_u32 s34, s44, 0x104e00
	s_addc_u32 s35, s45, 0
	s_add_u32 s36, s44, 0x104f00
	s_addc_u32 s37, s45, 0
	v_readlane_b32 s42, v249, 0
	s_add_u32 s38, s44, 0x105000
	v_readlane_b32 s43, v249, 1
	s_addc_u32 s39, s45, 0
	s_load_dwordx2 s[2:3], s[42:43], 0x4
	s_add_u32 s40, s44, 0x105100
	s_addc_u32 s41, s45, 0
	s_add_u32 s42, s44, 0x105200
	s_addc_u32 s43, s45, 0
	s_add_u32 s44, s44, 0x105300
	s_waitcnt lgkmcnt(0)
	s_mul_i32 s2, s2, s85
	s_addc_u32 s45, s45, 0
	s_mul_i32 s2, s2, s3
	s_mov_b32 s3, 1
	v_mov_b32_e32 v18, 0
	s_branch .LBB0_222

; __device__ __forceinline__ unsigned xb_ld(unsigned* p)              { return __hip_atomic_load(p, __ATOMIC_RELAXED, __HIP_MEMORY_SCOPE_AGENT); }
; #define XB_SPIN(cond, bar) do { unsigned _sp = 0; while (cond) { __builtin_amdgcn_s_sleep(1); \
;     if ((++_sp & 255u) == 0u) { if (xb_ld(&(bar)[XB_TMO])) break; if (_sp > XB_SPIN_CAP) { atomicAdd(&(bar)[XB_TMO], 1u); break; } } } } while (0)
; __device__ __forceinline__ void xcd_barrier(const XcdBarrier& b) {
;     ...
;         } else {
;             XB_SPIN(xb_ld(&bar[XB_XGEN(b.x)]) == gen, bar);
;             __builtin_amdgcn_fence(__ATOMIC_ACQUIRE, "agent");
;             asm volatile("s_waitcnt vmcnt(0)" ::: "memory");
.LBB0_249:
	s_or_b64 exec, exec, s[14:15]
	s_waitcnt vmcnt(0)
	s_waitcnt vmcnt(0)

; __device__ __forceinline__ unsigned xb_ld(unsigned* p)              { return __hip_atomic_load(p, __ATOMIC_RELAXED, __HIP_MEMORY_SCOPE_AGENT); }
; __device__ __forceinline__ unsigned xb_add(unsigned* p, unsigned v) { return __hip_atomic_fetch_add(p, v, __ATOMIC_RELAXED, __HIP_MEMORY_SCOPE_AGENT); }
; #define XB_SPIN(cond, bar) do { unsigned _sp = 0; while (cond) { __builtin_amdgcn_s_sleep(1); \
;     if ((++_sp & 255u) == 0u) { if (xb_ld(&(bar)[XB_TMO])) break; if (_sp > XB_SPIN_CAP) { atomicAdd(&(bar)[XB_TMO], 1u); break; } } } } while (0)
; __device__ __forceinline__ void xcd_barrier(const XcdBarrier& b) {
;     ...
;             __builtin_amdgcn_fence(__ATOMIC_RELEASE, "agent");
;             asm volatile("s_waitcnt vmcnt(0)" ::: "memory");
;             const unsigned og = xb_add(&bar[XB_TOP], 1u);
;             const unsigned tg = og / nx;
;             if (og + 1u == (tg + 1u) * nx) xb_add(&bar[XB_TOPGEN], 1u);
;             else XB_SPIN(xb_ld(&bar[XB_TOPGEN]) == tg, bar);
;             __builtin_amdgcn_fence(__ATOMIC_ACQUIRE, "agent");
;             xb_add(&bar[XB_XGEN(b.x)], 1u);
;             asm volatile("s_waitcnt vmcnt(0)" ::: "memory");
.LBB0_267:
	s_or_b64 exec, exec, s[8:9]
	s_mov_b64 s[8:9], exec
	v_mbcnt_lo_u32_b32 v2, s8, 0
	v_mbcnt_hi_u32_b32 v2, s9, v2
	v_cmp_eq_u32_e32 vcc, 0, v2
	s_waitcnt vmcnt(0)
	s_and_saveexec_b64 s[12:13], vcc
	s_cbranch_execz .LBB0_269
	s_bcnt1_i32_b64 s2, s[8:9]
	v_mov_b32_e32 v2, 0
	v_mov_b32_e32 v3, s2
	global_atomic_add v2, v3, s[10:11]

; __device__ __forceinline__ void xcd_barrier(const XcdBarrier& b) {
;     asm volatile("s_waitcnt vmcnt(0)" ::: "memory");
;     __syncthreads();
;     if (threadIdx.x == 0) {
;         unsigned* bar = b.bar;
;         __builtin_amdgcn_s_waitcnt(0);
;         unsigned nloc = b.st[0], nx = b.st[1];
;         if (nloc == 0u) { xcd_barrier_complete(bar, b.x, nloc, nx); b.st[0] = nloc; b.st[1] = nx; }
.LBB0_550:
	s_add_i32 s0, s68, 2
	s_mov_b32 s4, s68
	s_cmp_ge_i32 s0, s47
	s_cbranch_scc1 .LBB0_604
	s_waitcnt vmcnt(0)
	s_waitcnt vmcnt(0)
	s_barrier
	s_mov_b64 s[0:1], exec
	v_readlane_b32 s2, v249, 5
	v_readlane_b32 s3, v249, 6
	s_and_b64 s[2:3], s[0:1], s[2:3]
	s_mov_b64 exec, s[2:3]
	s_cbranch_execz .LBB0_603
	v_readlane_b32 s2, v255, 7
	s_waitcnt vmcnt(0) expcnt(0) lgkmcnt(0)
	buffer_inv sc1
	s_nop 0
	v_mov_b32_e32 v2, s2
	ds_read_b32 v4, v2
	v_readlane_b32 s2, v255, 8
	s_waitcnt lgkmcnt(0)
	v_cmp_ne_u32_e32 vcc, 0, v4
	v_mov_b32_e32 v2, s2
	ds_read_b32 v2, v2
	s_cbranch_vccnz .LBB0_567
	v_readlane_b32 s4, v249, 0
	v_readlane_b32 s5, v249, 1
	s_load_dwordx2 s[2:3], s[4:5], 0x4
	s_waitcnt lgkmcnt(0)
	s_mul_i32 s2, s2, s85
	s_mul_i32 s2, s2, s3
	s_mov_b32 s3, 1
	s_branch .LBB0_555

; __device__ __forceinline__ unsigned xb_ld(unsigned* p)              { return __hip_atomic_load(p, __ATOMIC_RELAXED, __HIP_MEMORY_SCOPE_AGENT); }
; #define XB_SPIN(cond, bar) do { unsigned _sp = 0; while (cond) { __builtin_amdgcn_s_sleep(1); \
;     if ((++_sp & 255u) == 0u) { if (xb_ld(&(bar)[XB_TMO])) break; if (_sp > XB_SPIN_CAP) { atomicAdd(&(bar)[XB_TMO], 1u); break; } } } } while (0)
; __device__ __forceinline__ void xcd_barrier(const XcdBarrier& b) {
;     ...
;         } else {
;             XB_SPIN(xb_ld(&bar[XB_XGEN(b.x)]) == gen, bar);
;             __builtin_amdgcn_fence(__ATOMIC_ACQUIRE, "agent");
;             asm volatile("s_waitcnt vmcnt(0)" ::: "memory");
.LBB0_582:
	s_or_b64 exec, exec, s[6:7]
	s_waitcnt vmcnt(0)
	s_waitcnt vmcnt(0)

; __device__ __forceinline__ unsigned xb_ld(unsigned* p)              { return __hip_atomic_load(p, __ATOMIC_RELAXED, __HIP_MEMORY_SCOPE_AGENT); }
; __device__ __forceinline__ unsigned xb_add(unsigned* p, unsigned v) { return __hip_atomic_fetch_add(p, v, __ATOMIC_RELAXED, __HIP_MEMORY_SCOPE_AGENT); }
; #define XB_SPIN(cond, bar) do { unsigned _sp = 0; while (cond) { __builtin_amdgcn_s_sleep(1); \
;     if ((++_sp & 255u) == 0u) { if (xb_ld(&(bar)[XB_TMO])) break; if (_sp > XB_SPIN_CAP) { atomicAdd(&(bar)[XB_TMO], 1u); break; } } } } while (0)
; __device__ __forceinline__ void xcd_barrier(const XcdBarrier& b) {
;     ...
;             __builtin_amdgcn_fence(__ATOMIC_RELEASE, "agent");
;             asm volatile("s_waitcnt vmcnt(0)" ::: "memory");
;             const unsigned og = xb_add(&bar[XB_TOP], 1u);
;             const unsigned tg = og / nx;
;             if (og + 1u == (tg + 1u) * nx) xb_add(&bar[XB_TOPGEN], 1u);
;             else XB_SPIN(xb_ld(&bar[XB_TOPGEN]) == tg, bar);
;             __builtin_amdgcn_fence(__ATOMIC_ACQUIRE, "agent");
;             xb_add(&bar[XB_XGEN(b.x)], 1u);
;             asm volatile("s_waitcnt vmcnt(0)" ::: "memory");
.LBB0_600:
	s_or_b64 exec, exec, s[4:5]
	s_mov_b64 s[4:5], exec
	v_mbcnt_lo_u32_b32 v2, s4, 0
	v_mbcnt_hi_u32_b32 v2, s5, v2
	v_cmp_eq_u32_e32 vcc, 0, v2
	s_waitcnt vmcnt(0)
	s_and_saveexec_b64 s[6:7], vcc
	s_cbranch_execz .LBB0_602
	s_bcnt1_i32_b64 s2, s[4:5]
	v_mov_b32_e32 v2, s2
	v_readlane_b32 s2, v251, 7
	v_readlane_b32 s3, v251, 8
	s_nop 4
	global_atomic_add v131, v2, s[2:3]

; __device__ __forceinline__ void xcd_barrier(const XcdBarrier& b) {
;     asm volatile("s_waitcnt vmcnt(0)" ::: "memory");
;     __syncthreads();
;     if (threadIdx.x == 0) {
;         unsigned* bar = b.bar;
;         __builtin_amdgcn_s_waitcnt(0);
;         unsigned nloc = b.st[0], nx = b.st[1];
;         if (nloc == 0u) { xcd_barrier_complete(bar, b.x, nloc, nx); b.st[0] = nloc; b.st[1] = nx; }
.LBB0_659:
	v_readlane_b32 s0, v255, 41
	s_add_i32 s2, s0, 4
	s_cmp_ge_i32 s2, s47
	s_cbranch_scc1 .LBB0_752
	s_waitcnt vmcnt(0)
	s_waitcnt vmcnt(0)
	s_barrier
	s_mov_b64 s[0:1], exec
	v_readlane_b32 s4, v249, 5
	v_readlane_b32 s5, v249, 6
	s_and_b64 s[4:5], s[0:1], s[4:5]
	s_mov_b64 exec, s[4:5]
	s_cbranch_execz .LBB0_751
	v_readlane_b32 s3, v255, 7
	s_waitcnt vmcnt(0) expcnt(0) lgkmcnt(0)
	buffer_inv sc1
	s_nop 0
	v_mov_b32_e32 v2, s3
	ds_read_b32 v4, v2
	v_readlane_b32 s3, v255, 8
	s_waitcnt lgkmcnt(0)
	v_cmp_ne_u32_e32 vcc, 0, v4
	v_mov_b32_e32 v2, s3
	ds_read_b32 v2, v2
	s_cbranch_vccnz .LBB0_715
	v_readlane_b32 s6, v249, 0
	v_readlane_b32 s7, v249, 1
	s_load_dwordx2 s[4:5], s[6:7], 0x4
	s_mov_b32 s14, 1
	s_waitcnt lgkmcnt(0)
	s_mul_i32 s3, s4, s85
	s_mul_i32 s3, s3, s5
	s_branch .LBB0_703

; __device__ __forceinline__ unsigned xb_ld(unsigned* p)              { return __hip_atomic_load(p, __ATOMIC_RELAXED, __HIP_MEMORY_SCOPE_AGENT); }
; __device__ __forceinline__ unsigned xb_add(unsigned* p, unsigned v) { return __hip_atomic_fetch_add(p, v, __ATOMIC_RELAXED, __HIP_MEMORY_SCOPE_AGENT); }
; #define XB_SPIN(cond, bar) do { unsigned _sp = 0; while (cond) { __builtin_amdgcn_s_sleep(1); \
;     if ((++_sp & 255u) == 0u) { if (xb_ld(&(bar)[XB_TMO])) break; if (_sp > XB_SPIN_CAP) { atomicAdd(&(bar)[XB_TMO], 1u); break; } } } } while (0)
; __device__ __forceinline__ void xcd_barrier(const XcdBarrier& b) {
;     ...
;             __builtin_amdgcn_fence(__ATOMIC_RELEASE, "agent");
;             asm volatile("s_waitcnt vmcnt(0)" ::: "memory");
;             const unsigned og = xb_add(&bar[XB_TOP], 1u);
;             const unsigned tg = og / nx;
;             if (og + 1u == (tg + 1u) * nx) xb_add(&bar[XB_TOPGEN], 1u);
;             else XB_SPIN(xb_ld(&bar[XB_TOPGEN]) == tg, bar);
;             __builtin_amdgcn_fence(__ATOMIC_ACQUIRE, "agent");
;             xb_add(&bar[XB_XGEN(b.x)], 1u);
;             asm volatile("s_waitcnt vmcnt(0)" ::: "memory");
.LBB0_748:
	s_or_b64 exec, exec, s[4:5]
	s_mov_b64 s[4:5], exec
	v_mbcnt_lo_u32_b32 v2, s4, 0
	v_mbcnt_hi_u32_b32 v2, s5, v2
	v_cmp_eq_u32_e32 vcc, 0, v2
	s_waitcnt vmcnt(0)
	s_and_saveexec_b64 s[6:7], vcc
	s_cbranch_execz .LBB0_750
	s_bcnt1_i32_b64 s3, s[4:5]
	v_readlane_b32 s4, v251, 7
	v_mov_b32_e32 v2, s3
	v_readlane_b32 s5, v251, 8
	s_nop 4
	global_atomic_add v131, v2, s[4:5]

; __device__ __forceinline__ void xcd_barrier(const XcdBarrier& b) {
;     asm volatile("s_waitcnt vmcnt(0)" ::: "memory");
;     __syncthreads();
;     if (threadIdx.x == 0) {
;         unsigned* bar = b.bar;
;         __builtin_amdgcn_s_waitcnt(0);
;         unsigned nloc = b.st[0], nx = b.st[1];
;         if (nloc == 0u) { xcd_barrier_complete(bar, b.x, nloc, nx); b.st[0] = nloc; b.st[1] = nx; }
.LBB0_1029:
	v_readlane_b32 s0, v255, 41
	s_add_i32 s2, s0, 5
	s_cmp_ge_i32 s2, s47
	s_cbranch_scc1 .LBB0_1041
	s_waitcnt vmcnt(0)
	s_waitcnt vmcnt(0) lgkmcnt(0)
	s_barrier
	s_mov_b64 s[0:1], exec
	v_readlane_b32 s4, v249, 5
	v_readlane_b32 s5, v249, 6
	s_and_b64 s[4:5], s[0:1], s[4:5]
	v_readlane_b32 s29, v255, 31
	v_readlane_b32 s95, v255, 35
	v_readlane_b32 s96, v255, 36
	s_mov_b64 exec, s[4:5]
	s_cbranch_execz .LBB0_1083
	v_readlane_b32 s3, v255, 7
	s_waitcnt vmcnt(0) expcnt(0) lgkmcnt(0)
	buffer_inv sc1
	s_nop 0
	v_mov_b32_e32 v2, s3
	ds_read_b32 v4, v2
	v_readlane_b32 s3, v255, 8
	s_waitcnt lgkmcnt(0)
	v_cmp_ne_u32_e32 vcc, 0, v4
	v_mov_b32_e32 v2, s3
	ds_read_b32 v2, v2
	s_cbranch_vccnz .LBB0_1047
	v_readlane_b32 s6, v249, 0
	v_readlane_b32 s7, v249, 1
	s_load_dwordx2 s[4:5], s[6:7], 0x4
	s_mov_b32 s14, 1
	s_waitcnt lgkmcnt(0)
	s_mul_i32 s3, s4, s85
	s_mul_i32 s3, s3, s5
	s_branch .LBB0_1034

; __device__ __forceinline__ void xcd_barrier(const XcdBarrier& b) {
;     asm volatile("s_waitcnt vmcnt(0)" ::: "memory");
;     __syncthreads();
;     if (threadIdx.x == 0) {
;         unsigned* bar = b.bar;
;         __builtin_amdgcn_s_waitcnt(0);
;         unsigned nloc = b.st[0], nx = b.st[1];
;         if (nloc == 0u) { xcd_barrier_complete(bar, b.x, nloc, nx); b.st[0] = nloc; b.st[1] = nx; }
; __global__ void __launch_bounds__(512, 2) mk_fwd(Args args) {
;     ...
;                 if (!MK_MULTI) xcd_barrier(bar);
.LBB0_1090:
	s_or_b64 exec, exec, s[0:1]
	s_waitcnt vmcnt(0)
	s_waitcnt lgkmcnt(0)
	s_barrier
	s_mov_b64 s[0:1], exec
	v_readlane_b32 s2, v249, 5
	v_readlane_b32 s3, v249, 6
	s_and_b64 s[2:3], s[0:1], s[2:3]
	s_mov_b64 exec, s[2:3]
	s_cbranch_execz .LBB0_1142
	v_readlane_b32 s2, v255, 7
	s_waitcnt vmcnt(0) expcnt(0) lgkmcnt(0)
	buffer_inv sc1
	s_nop 0
	v_mov_b32_e32 v2, s2
	ds_read_b32 v4, v2
	v_readlane_b32 s2, v255, 8
	s_waitcnt lgkmcnt(0)
	v_cmp_ne_u32_e32 vcc, 0, v4
	v_mov_b32_e32 v2, s2
	ds_read_b32 v2, v2
	s_cbranch_vccnz .LBB0_1106
	v_readlane_b32 s4, v249, 0
	v_readlane_b32 s5, v249, 1
	s_load_dwordx2 s[2:3], s[4:5], 0x4
	s_waitcnt lgkmcnt(0)
	s_mul_i32 s2, s2, s85
	s_mul_i32 s2, s2, s3
	s_mov_b32 s3, 1
	s_branch .LBB0_1094

; __device__ __forceinline__ void xcd_barrier(const XcdBarrier& b) {
;     asm volatile("s_waitcnt vmcnt(0)" ::: "memory");
;     __syncthreads();
;     if (threadIdx.x == 0) {
;         unsigned* bar = b.bar;
;         __builtin_amdgcn_s_waitcnt(0);
;         unsigned nloc = b.st[0], nx = b.st[1];
;         if (nloc == 0u) { xcd_barrier_complete(bar, b.x, nloc, nx); b.st[0] = nloc; b.st[1] = nx; }
.LBB0_1180:
	v_readlane_b32 s0, v255, 41
	s_add_i32 s2, s0, 6
	s_cmp_ge_i32 s2, s47
	s_cbranch_scc1 .LBB0_1234
	s_waitcnt vmcnt(0)
	s_waitcnt vmcnt(0) lgkmcnt(0)
	s_barrier
	s_mov_b64 s[0:1], exec
	v_readlane_b32 s4, v249, 5
	v_readlane_b32 s5, v249, 6
	s_and_b64 s[4:5], s[0:1], s[4:5]
	s_mov_b64 exec, s[4:5]
	s_cbranch_execz .LBB0_1233
	v_readlane_b32 s3, v255, 7
	s_waitcnt vmcnt(0) expcnt(0) lgkmcnt(0)
	buffer_inv sc1
	s_nop 0
	v_mov_b32_e32 v2, s3
	ds_read_b32 v4, v2
	v_readlane_b32 s3, v255, 8
	s_waitcnt lgkmcnt(0)
	v_cmp_ne_u32_e32 vcc, 0, v4
	v_mov_b32_e32 v2, s3
	ds_read_b32 v2, v2
	s_cbranch_vccnz .LBB0_1197
	v_readlane_b32 s6, v249, 0
	v_readlane_b32 s7, v249, 1
	s_load_dwordx2 s[4:5], s[6:7], 0x4
	s_mov_b32 s14, 1
	s_waitcnt lgkmcnt(0)
	s_mul_i32 s3, s4, s85
	s_mul_i32 s3, s3, s5
	s_branch .LBB0_1185

; __device__ __forceinline__ void xcd_barrier(const XcdBarrier& b) {
;     asm volatile("s_waitcnt vmcnt(0)" ::: "memory");
;     __syncthreads();
;     if (threadIdx.x == 0) {
;         unsigned* bar = b.bar;
;         __builtin_amdgcn_s_waitcnt(0);
;         unsigned nloc = b.st[0], nx = b.st[1];
;         if (nloc == 0u) { xcd_barrier_complete(bar, b.x, nloc, nx); b.st[0] = nloc; b.st[1] = nx; }
.LBB0_1268:
	v_readlane_b32 s0, v255, 41
	s_add_i32 s2, s0, 7
	s_cmp_ge_i32 s2, s47
	s_cbranch_scc1 .LBB0_1322
	s_waitcnt vmcnt(0)
	s_waitcnt lgkmcnt(0)
	s_barrier
	s_mov_b64 s[0:1], exec
	v_readlane_b32 s4, v249, 5
	v_readlane_b32 s5, v249, 6
	s_and_b64 s[4:5], s[0:1], s[4:5]
	s_mov_b64 exec, s[4:5]
	s_cbranch_execz .LBB0_1321
	v_readlane_b32 s3, v255, 7
	s_waitcnt vmcnt(0) expcnt(0) lgkmcnt(0)
	buffer_inv sc1
	s_nop 0
	v_mov_b32_e32 v2, s3
	ds_read_b32 v4, v2
	v_readlane_b32 s3, v255, 8
	s_waitcnt lgkmcnt(0)
	v_cmp_ne_u32_e32 vcc, 0, v4
	v_mov_b32_e32 v2, s3
	ds_read_b32 v2, v2
	s_cbranch_vccnz .LBB0_1285
	v_readlane_b32 s6, v249, 0
	v_readlane_b32 s7, v249, 1
	s_load_dwordx2 s[4:5], s[6:7], 0x4
	s_mov_b32 s14, 1
	s_waitcnt lgkmcnt(0)
	s_mul_i32 s3, s4, s85
	s_mul_i32 s3, s3, s5
	s_branch .LBB0_1273

; __device__ __forceinline__ void xcd_barrier(const XcdBarrier& b) {
;     asm volatile("s_waitcnt vmcnt(0)" ::: "memory");
;     __syncthreads();
;     if (threadIdx.x == 0) {
;         unsigned* bar = b.bar;
;         __builtin_amdgcn_s_waitcnt(0);
;         unsigned nloc = b.st[0], nx = b.st[1];
;         if (nloc == 0u) { xcd_barrier_complete(bar, b.x, nloc, nx); b.st[0] = nloc; b.st[1] = nx; }
.LBB0_1505:
	v_readlane_b32 s0, v255, 41
	s_add_i32 s2, s0, 8
	s_cmp_ge_i32 s2, s47
	s_cbranch_scc1 .LBB0_1517
	s_waitcnt vmcnt(0)
	s_waitcnt lgkmcnt(0)
	s_barrier
	s_mov_b64 s[0:1], exec
	v_readlane_b32 s4, v249, 5
	v_readlane_b32 s5, v249, 6
	s_and_b64 s[4:5], s[0:1], s[4:5]
	v_readlane_b32 s29, v255, 31
	v_readlane_b32 s95, v255, 35
	v_readlane_b32 s96, v255, 36
	s_mov_b64 exec, s[4:5]
	s_cbranch_execz .LBB0_1559
	v_readlane_b32 s3, v255, 7
	s_waitcnt vmcnt(0) expcnt(0) lgkmcnt(0)
	buffer_inv sc1
	s_nop 0
	v_mov_b32_e32 v2, s3
	ds_read_b32 v4, v2
	v_readlane_b32 s3, v255, 8
	s_waitcnt lgkmcnt(0)
	v_cmp_ne_u32_e32 vcc, 0, v4
	v_mov_b32_e32 v2, s3
	ds_read_b32 v2, v2
	s_cbranch_vccnz .LBB0_1523
	v_readlane_b32 s6, v249, 0
	v_readlane_b32 s7, v249, 1
	s_load_dwordx2 s[4:5], s[6:7], 0x4
	s_mov_b32 s14, 1
	s_waitcnt lgkmcnt(0)
	s_mul_i32 s3, s4, s85
	s_mul_i32 s3, s3, s5
	s_branch .LBB0_1510

; __device__ __forceinline__ void xcd_barrier(const XcdBarrier& b) {
;     asm volatile("s_waitcnt vmcnt(0)" ::: "memory");
;     __syncthreads();
;     if (threadIdx.x == 0) {
;         unsigned* bar = b.bar;
;         __builtin_amdgcn_s_waitcnt(0);
;         unsigned nloc = b.st[0], nx = b.st[1];
;         if (nloc == 0u) { xcd_barrier_complete(bar, b.x, nloc, nx); b.st[0] = nloc; b.st[1] = nx; }
.LBB0_1629:
	v_readlane_b32 s0, v255, 41
	s_add_i32 s2, s0, 9
	s_cmp_ge_i32 s2, s47
	s_cbranch_scc1 .LBB0_1683
	s_waitcnt vmcnt(0)
	s_waitcnt lgkmcnt(0)
	s_barrier
	s_mov_b64 s[0:1], exec
	v_readlane_b32 s4, v249, 5
	v_readlane_b32 s5, v249, 6
	s_and_b64 s[4:5], s[0:1], s[4:5]
	s_mov_b64 exec, s[4:5]
	s_cbranch_execz .LBB0_1682
	v_readlane_b32 s3, v255, 7
	s_waitcnt vmcnt(0) expcnt(0) lgkmcnt(0)
	buffer_inv sc1
	s_nop 0
	v_mov_b32_e32 v2, s3
	ds_read_b32 v4, v2
	v_readlane_b32 s3, v255, 8
	s_waitcnt lgkmcnt(0)
	v_cmp_ne_u32_e32 vcc, 0, v4
	v_mov_b32_e32 v2, s3
	ds_read_b32 v2, v2
	s_cbranch_vccnz .LBB0_1646
	v_readlane_b32 s6, v249, 0
	v_readlane_b32 s7, v249, 1
	s_load_dwordx2 s[4:5], s[6:7], 0x4
	s_mov_b32 s14, 1
	s_waitcnt lgkmcnt(0)
	s_mul_i32 s3, s4, s85
	s_mul_i32 s3, s3, s5
	s_branch .LBB0_1634

; __device__ __forceinline__ void xcd_barrier(const XcdBarrier& b) {
;     asm volatile("s_waitcnt vmcnt(0)" ::: "memory");
;     __syncthreads();
;     if (threadIdx.x == 0) {
;         unsigned* bar = b.bar;
;         __builtin_amdgcn_s_waitcnt(0);
;         unsigned nloc = b.st[0], nx = b.st[1];
;         if (nloc == 0u) { xcd_barrier_complete(bar, b.x, nloc, nx); b.st[0] = nloc; b.st[1] = nx; }
.LBB0_1729:
	v_readlane_b32 s2, v255, 7
	s_waitcnt vmcnt(0) expcnt(0) lgkmcnt(0)
	buffer_inv sc1
	s_nop 0
	v_mov_b32_e32 v2, s2
	ds_read_b32 v4, v2
	v_readlane_b32 s2, v255, 8
	s_waitcnt lgkmcnt(0)
	v_cmp_ne_u32_e32 vcc, 0, v4
	v_mov_b32_e32 v2, s2
	ds_read_b32 v2, v2
	s_cbranch_vccnz .LBB0_1744
	v_readlane_b32 s4, v249, 0
	v_readlane_b32 s5, v249, 1
	s_load_dwordx2 s[2:3], s[4:5], 0x4
	s_waitcnt lgkmcnt(0)
	s_mul_i32 s2, s2, s85
	s_mul_i32 s2, s2, s3
	s_mov_b32 s3, 1
	s_branch .LBB0_1732

; __device__ __forceinline__ unsigned xb_ld(unsigned* p)              { return __hip_atomic_load(p, __ATOMIC_RELAXED, __HIP_MEMORY_SCOPE_AGENT); }
; __device__ __forceinline__ unsigned xb_add(unsigned* p, unsigned v) { return __hip_atomic_fetch_add(p, v, __ATOMIC_RELAXED, __HIP_MEMORY_SCOPE_AGENT); }
; #define XB_SPIN(cond, bar) do { unsigned _sp = 0; while (cond) { __builtin_amdgcn_s_sleep(1); \
;     if ((++_sp & 255u) == 0u) { if (xb_ld(&(bar)[XB_TMO])) break; if (_sp > XB_SPIN_CAP) { atomicAdd(&(bar)[XB_TMO], 1u); break; } } } } while (0)
; __device__ __forceinline__ void xcd_barrier(const XcdBarrier& b) {
;     ...
;             __builtin_amdgcn_fence(__ATOMIC_RELEASE, "agent");
;             asm volatile("s_waitcnt vmcnt(0)" ::: "memory");
;             const unsigned og = xb_add(&bar[XB_TOP], 1u);
;             const unsigned tg = og / nx;
;             if (og + 1u == (tg + 1u) * nx) xb_add(&bar[XB_TOPGEN], 1u);
;             else XB_SPIN(xb_ld(&bar[XB_TOPGEN]) == tg, bar);
;             __builtin_amdgcn_fence(__ATOMIC_ACQUIRE, "agent");
;             xb_add(&bar[XB_XGEN(b.x)], 1u);
;             asm volatile("s_waitcnt vmcnt(0)" ::: "memory");
.LBB0_1777:
	s_or_b64 exec, exec, s[4:5]
	s_mov_b64 s[4:5], exec
	v_mbcnt_lo_u32_b32 v2, s4, 0
	v_mbcnt_hi_u32_b32 v2, s5, v2
	v_cmp_eq_u32_e32 vcc, 0, v2
	s_waitcnt vmcnt(0)
	s_and_saveexec_b64 s[6:7], vcc
	s_cbranch_execnz .LBB0_1778
	s_getpc_b64 s[98:99]
